# attn: batched k_norm_g loads + prefetch kept in flight; no cross-queue stealing; hand-scheduled unmasked fixed-ref kt loop
# speedup vs baseline: 1.0082x; 1.0082x over previous
.LBB0_392:
	s_add_i32 s68, s68, 1
	s_cmp_eq_u32 s68, 1
	s_cbranch_scc1 .LBB0_457

.LBB0_406:
	s_add_i32 s73, s73, 1
	s_cmp_lg_u32 s73, 5
	s_cbranch_scc0 .LBB0_394
	s_waitcnt vmcnt(0)
	v_mov_b64_e32 v[88:89], v[160:161]
	v_mov_b64_e32 v[92:93], v[164:165]
	v_mov_b64_e32 v[84:85], v[172:173]
	v_mov_b64_e32 v[80:81], v[168:169]
	v_mov_b32_e32 v113, v236
	v_mov_b32_e32 v112, v237
	v_mov_b64_e32 v[90:91], v[162:163]
	v_mov_b64_e32 v[94:95], v[166:167]
	v_mov_b64_e32 v[86:87], v[174:175]
	v_mov_b64_e32 v[82:83], v[170:171]
	s_mov_b64 s[6:7], -1
	s_cmp_lt_u32 s73, 2
	s_mov_b32 s8, 0
	s_cbranch_scc0 .LBB0_402
.LBB0_408:
	s_and_b64 vcc, exec, s[6:7]
	s_cbranch_vccz .LBB0_405
	s_and_b32 s6, s73, 3
	s_cmp_eq_u32 s6, 0
	s_cselect_b64 s[6:7], -1, 0
	s_add_i32 s58, s84, s73
	s_cmp_lt_u32 s58, 32
	s_cselect_b64 s[58:59], -1, 0
	s_or_b64 s[6:7], s[6:7], s[58:59]
	s_and_b64 s[6:7], s[6:7], exec
	s_cselect_b32 s62, 1, 2
	s_add_i32 s62, s62, s73
	s_waitcnt vmcnt(1)
	v_mov_b64_e32 v[170:171], v[82:83]
	s_waitcnt vmcnt(0)
	v_mov_b64_e32 v[174:175], v[86:87]
	v_mov_b64_e32 v[166:167], v[94:95]
	v_mov_b64_e32 v[162:163], v[90:91]
	v_mov_b32_e32 v96, v225
	v_mov_b32_e32 v97, v226
	s_cmp_gt_u32 s62, 4
	v_mov_b64_e32 v[168:169], v[80:81]
	v_mov_b64_e32 v[172:173], v[84:85]
	v_mov_b64_e32 v[164:165], v[92:93]
	v_mov_b64_e32 v[160:161], v[88:89]
	v_lshlrev_b32_e32 v110, 3, v97
	v_lshl_add_u32 v96, v96, 5, v110
	v_ashrrev_i32_e32 v97, 31, v96
	v_lshl_add_u64 v[96:97], v[96:97], 2, s[16:17]
	global_load_dwordx4 v[238:241], v[96:97], off
	global_load_dwordx4 v[242:245], v[96:97], off offset:16
	global_load_dwordx4 v[246:249], v[96:97], off offset:64
	global_load_dwordx4 v[250:253], v[96:97], off offset:80
	s_barrier
	s_waitcnt vmcnt(0)
	s_cbranch_scc1 .LBB0_415
	s_mov_b64 s[58:59], -1
	s_cmp_lt_u32 s62, 2
	s_mov_b64 s[6:7], s[52:53]
	s_cbranch_scc1 .LBB0_413
	s_add_i32 s62, s62, s72
	s_add_i32 s6, s62, -3
	s_cmp_lt_u32 s6, 32
	s_mov_b64 s[58:59], 0
	s_cbranch_scc0 .LBB0_413
	s_lshl_b32 s6, s62, 7
	s_addk_i32 s6, 0xfe80
	s_add_u32 s6, s0, s6
	s_addc_u32 s7, s1, 0
	s_mov_b64 s[58:59], -1

.LBB0_415:
	v_lshlrev_b32_e32 v116, 16, v92
	v_and_b32_e32 v108, 0xffff0000, v92
	v_lshlrev_b32_e32 v117, 16, v88
	v_and_b32_e32 v109, 0xffff0000, v88
	v_lshlrev_b32_e32 v102, 16, v93
	v_and_b32_e32 v106, 0xffff0000, v93
	v_lshlrev_b32_e32 v104, 16, v94
	v_and_b32_e32 v100, 0xffff0000, v94
	v_lshlrev_b32_e32 v92, 16, v95
	v_and_b32_e32 v88, 0xffff0000, v95
	v_mov_b32_e32 v94, v116
	v_mov_b32_e32 v95, v108
	v_lshlrev_b32_e32 v103, 16, v89
	v_and_b32_e32 v107, 0xffff0000, v89
	v_lshlrev_b32_e32 v105, 16, v90
	v_and_b32_e32 v101, 0xffff0000, v90
	v_lshlrev_b32_e32 v93, 16, v91
	v_and_b32_e32 v89, 0xffff0000, v91
	v_mov_b32_e32 v90, v117
	v_mov_b32_e32 v91, v109
	v_pk_mul_f32 v[94:95], v[94:95], v[94:95]
	v_mov_b32_e32 v98, v106
	v_mov_b32_e32 v99, v102
	v_pk_fma_f32 v[90:91], v[90:91], v[90:91], v[94:95]
	v_mov_b32_e32 v94, v107
	v_mov_b32_e32 v95, v103
	v_pk_mul_f32 v[98:99], v[98:99], v[98:99]
	v_mov_b32_e32 v118, v100
	v_pk_fma_f32 v[94:95], v[94:95], v[94:95], v[98:99]
	v_mov_b32_e32 v119, v104
	v_add_f32_e32 v90, v90, v91
	v_mov_b32_e32 v98, v101
	v_mov_b32_e32 v99, v105
	v_pk_mul_f32 v[118:119], v[118:119], v[118:119]
	v_add_f32_e32 v90, v95, v90
	v_pk_fma_f32 v[98:99], v[98:99], v[98:99], v[118:119]
	v_mov_b32_e32 v120, v88
	v_mov_b32_e32 v121, v92
	v_add_f32_e32 v90, v94, v90
	v_mov_b32_e32 v118, v89
	v_mov_b32_e32 v119, v93
	v_pk_mul_f32 v[120:121], v[120:121], v[120:121]
	v_add_f32_e32 v90, v99, v90
	v_pk_fma_f32 v[118:119], v[118:119], v[118:119], v[120:121]
	v_add_f32_e32 v90, v98, v90
	v_add_f32_e32 v90, v119, v90
	v_add_f32_e32 v90, v118, v90
	ds_bpermute_b32 v91, v223, v90
	v_add_u32_e32 v94, s8, v200
	v_ashrrev_i32_e32 v95, 6, v94
	v_cvt_f32_i32_e32 v95, v95
	s_cmp_gt_u32 s73, 1
	s_waitcnt lgkmcnt(0)
	v_add_f32_e32 v90, v90, v91
	ds_bpermute_b32 v91, v224, v90
	s_cselect_b64 s[58:59], -1, 0
	s_cmp_lt_u32 s73, 2
	s_waitcnt lgkmcnt(0)
	v_add_f32_e32 v90, v90, v91
	v_fmamk_f32 v90, v90, 0x3c800000, v211
	v_mul_f32_e32 v91, 0x4b800000, v90
	v_cmp_gt_f32_e32 vcc, s33, v90
	s_nop 1
	v_cndmask_b32_e32 v90, v90, v91, vcc
	v_rsq_f32_e32 v90, v90
	s_nop 0
	v_mul_f32_e32 v91, 0x45800000, v90
	v_cndmask_b32_e32 v98, v90, v91, vcc
	v_and_b32_e32 v90, 63, v94
	v_cvt_f32_ubyte0_e32 v90, v90
	v_cndmask_b32_e64 v111, v90, v95, s[4:5]
	v_pk_mul_f32 v[90:91], v[98:99], v[116:117] op_sel_hi:[0,1]
	v_mul_f32_e32 v90, v246, v90
	v_mul_f32_e32 v91, v238, v91
	s_cbranch_scc1 .LBB0_417
	v_cvt_f32_i32_e32 v94, v110
	v_mul_f32_e32 v94, 0xbf549a78, v94
	v_exp_f32_e32 v94, v94
	s_nop 0
	v_mul_f32_e32 v94, v111, v94
	v_mul_f32_e32 v95, 0.15915494, v94
	v_sin_f32_e32 v114, v95
	v_cos_f32_e32 v94, v95
	v_pk_mul_f32 v[114:115], v[114:115], v[90:91] op_sel:[0,1] op_sel_hi:[0,0]
	v_pk_mul_f32 v[116:117], v[94:95], v[90:91] op_sel_hi:[0,1]
	v_pk_fma_f32 v[90:91], v[94:95], v[90:91], v[114:115] op_sel_hi:[0,1,1] neg_lo:[0,0,1] neg_hi:[0,0,1]
	v_add_f32_e32 v90, v116, v114
.LBB0_417:
	v_mov_b32_e32 v99, v98
	v_pk_mul_f32 v[108:109], v[98:99], v[108:109]
	v_cndmask_b32_e64 v114, 0, 1, s[58:59]
	v_cmp_ne_u32_e64 s[6:7], 1, v114
	s_andn2_b64 vcc, exec, s[58:59]
	v_mul_f32_e32 v94, v108, v247
	v_mul_f32_e32 v95, v109, v239
	s_cbranch_vccnz .LBB0_419
	v_or_b32_e32 v108, 1, v110
	v_cvt_f32_i32_e32 v108, v108
	v_mul_f32_e32 v108, 0xbf549a78, v108
	v_exp_f32_e32 v108, v108
	s_nop 0
	v_mul_f32_e32 v108, v111, v108
	v_mul_f32_e32 v109, 0.15915494, v108
	v_sin_f32_e32 v114, v109
	v_cos_f32_e32 v108, v109
	v_pk_mul_f32 v[114:115], v[114:115], v[94:95] op_sel:[0,1] op_sel_hi:[0,0]
	v_pk_mul_f32 v[116:117], v[108:109], v[94:95] op_sel_hi:[0,1]
	v_pk_fma_f32 v[94:95], v[108:109], v[94:95], v[114:115] op_sel_hi:[0,1,1] neg_lo:[0,0,1] neg_hi:[0,0,1]
	v_add_f32_e32 v94, v116, v114
.LBB0_419:
	v_pk_mul_f32 v[102:103], v[98:99], v[102:103]
	s_and_b64 vcc, exec, s[6:7]
	v_mul_f32_e32 v102, v102, v248
	v_mul_f32_e32 v103, v103, v240
	s_cbranch_vccnz .LBB0_421
	v_or_b32_e32 v108, 2, v110
	v_cvt_f32_i32_e32 v108, v108
	v_mul_f32_e32 v108, 0xbf549a78, v108
	v_exp_f32_e32 v108, v108
	s_nop 0
	v_mul_f32_e32 v108, v111, v108
	v_mul_f32_e32 v109, 0.15915494, v108
	v_sin_f32_e32 v114, v109
	v_cos_f32_e32 v108, v109
	v_pk_mul_f32 v[114:115], v[114:115], v[102:103] op_sel:[0,1] op_sel_hi:[0,0]
	v_pk_mul_f32 v[116:117], v[108:109], v[102:103] op_sel_hi:[0,1]
	v_pk_fma_f32 v[102:103], v[108:109], v[102:103], v[114:115] op_sel_hi:[0,1,1] neg_lo:[0,0,1] neg_hi:[0,0,1]
	v_add_f32_e32 v102, v116, v114
.LBB0_421:
	v_pk_mul_f32 v[106:107], v[98:99], v[106:107]
	s_and_b64 vcc, exec, s[6:7]
	v_mul_f32_e32 v106, v106, v249
	v_mul_f32_e32 v107, v107, v241
	s_cbranch_vccnz .LBB0_423
	v_or_b32_e32 v108, 3, v110
	v_cvt_f32_i32_e32 v108, v108
	v_mul_f32_e32 v108, 0xbf549a78, v108
	v_exp_f32_e32 v108, v108
	s_nop 0
	v_mul_f32_e32 v108, v111, v108
	v_mul_f32_e32 v109, 0.15915494, v108
	v_sin_f32_e32 v114, v109
	v_cos_f32_e32 v108, v109
	v_pk_mul_f32 v[114:115], v[114:115], v[106:107] op_sel:[0,1] op_sel_hi:[0,0]
	v_pk_mul_f32 v[116:117], v[108:109], v[106:107] op_sel_hi:[0,1]
	v_pk_fma_f32 v[106:107], v[108:109], v[106:107], v[114:115] op_sel_hi:[0,1,1] neg_lo:[0,0,1] neg_hi:[0,0,1]
	v_add_f32_e32 v106, v116, v114
.LBB0_423:
	v_pk_mul_f32 v[104:105], v[98:99], v[104:105]
	s_and_b64 vcc, exec, s[6:7]
	v_mul_f32_e32 v104, v104, v250
	v_mul_f32_e32 v105, v105, v242
	s_cbranch_vccnz .LBB0_425
	v_or_b32_e32 v108, 4, v110
	v_cvt_f32_i32_e32 v108, v108
	v_mul_f32_e32 v108, 0xbf549a78, v108
	v_exp_f32_e32 v108, v108
	s_nop 0
	v_mul_f32_e32 v108, v111, v108
	v_mul_f32_e32 v109, 0.15915494, v108
	v_sin_f32_e32 v114, v109
	v_cos_f32_e32 v108, v109
	v_pk_mul_f32 v[114:115], v[114:115], v[104:105] op_sel:[0,1] op_sel_hi:[0,0]
	v_pk_mul_f32 v[116:117], v[108:109], v[104:105] op_sel_hi:[0,1]
	v_pk_fma_f32 v[104:105], v[108:109], v[104:105], v[114:115] op_sel_hi:[0,1,1] neg_lo:[0,0,1] neg_hi:[0,0,1]
	v_add_f32_e32 v104, v116, v114
.LBB0_425:
	v_pk_mul_f32 v[100:101], v[98:99], v[100:101]
	s_and_b64 vcc, exec, s[6:7]
	v_mul_f32_e32 v100, v100, v251
	v_mul_f32_e32 v101, v101, v243
	s_cbranch_vccnz .LBB0_427
	v_or_b32_e32 v108, 5, v110
	v_cvt_f32_i32_e32 v108, v108
	v_mul_f32_e32 v108, 0xbf549a78, v108
	v_exp_f32_e32 v108, v108
	s_nop 0
	v_mul_f32_e32 v108, v111, v108
	v_mul_f32_e32 v109, 0.15915494, v108
	v_sin_f32_e32 v114, v109
	v_cos_f32_e32 v108, v109
	v_pk_mul_f32 v[114:115], v[114:115], v[100:101] op_sel:[0,1] op_sel_hi:[0,0]
	v_pk_mul_f32 v[116:117], v[108:109], v[100:101] op_sel_hi:[0,1]
	v_pk_fma_f32 v[100:101], v[108:109], v[100:101], v[114:115] op_sel_hi:[0,1,1] neg_lo:[0,0,1] neg_hi:[0,0,1]
	v_add_f32_e32 v100, v116, v114
.LBB0_427:
	v_pk_mul_f32 v[92:93], v[98:99], v[92:93]
	s_and_b64 vcc, exec, s[6:7]
	v_mul_f32_e32 v92, v92, v252
	v_mul_f32_e32 v93, v93, v244
	s_cbranch_vccnz .LBB0_429
	v_or_b32_e32 v108, 6, v110
	v_cvt_f32_i32_e32 v108, v108
	v_mul_f32_e32 v108, 0xbf549a78, v108
	v_exp_f32_e32 v108, v108
	s_nop 0
	v_mul_f32_e32 v108, v111, v108
	v_mul_f32_e32 v109, 0.15915494, v108
	v_sin_f32_e32 v114, v109
	v_cos_f32_e32 v108, v109
	v_pk_mul_f32 v[114:115], v[114:115], v[92:93] op_sel:[0,1] op_sel_hi:[0,0]
	v_pk_mul_f32 v[116:117], v[108:109], v[92:93] op_sel_hi:[0,1]
	v_pk_fma_f32 v[92:93], v[108:109], v[92:93], v[114:115] op_sel_hi:[0,1,1] neg_lo:[0,0,1] neg_hi:[0,0,1]
	v_add_f32_e32 v92, v116, v114
.LBB0_429:
	v_pk_mul_f32 v[88:89], v[98:99], v[88:89]
	s_and_b64 vcc, exec, s[6:7]
	v_mul_f32_e32 v88, v88, v253
	v_mul_f32_e32 v89, v89, v245
	s_cbranch_vccnz .LBB0_431
	v_or_b32_e32 v96, 7, v110
	v_cvt_f32_i32_e32 v96, v96
	v_mul_f32_e32 v96, 0xbf549a78, v96
	v_exp_f32_e32 v96, v96
	s_nop 0
	v_mul_f32_e32 v96, v111, v96
	v_mul_f32_e32 v97, 0.15915494, v96
	v_sin_f32_e32 v98, v97
	v_cos_f32_e32 v96, v97
	v_pk_mul_f32 v[98:99], v[98:99], v[88:89] op_sel:[0,1] op_sel_hi:[0,0]
	v_pk_mul_f32 v[108:109], v[96:97], v[88:89] op_sel_hi:[0,1]
	v_pk_fma_f32 v[88:89], v[96:97], v[88:89], v[98:99] op_sel_hi:[0,1,1] neg_lo:[0,0,1] neg_hi:[0,0,1]
	v_add_f32_e32 v88, v108, v98
.LBB0_431:
	s_cmp_eq_u32 s73, 2
	s_cselect_b64 s[58:59], -1, 0
	s_cmp_lg_u32 s73, 2
	v_cvt_pk_bf16_f32 v96, v91, v95
	v_cvt_pk_bf16_f32 v97, v103, v107
	s_cselect_b64 s[62:63], -1, 0
	s_cmp_eq_u32 s73, 4
	v_cvt_pk_bf16_f32 v98, v105, v101
	v_cvt_pk_bf16_f32 v99, v93, v89
	ds_write_b128 v233, v[96:99]
	v_cvt_pk_bf16_f32 v94, v90, v94
	v_cvt_pk_bf16_f32 v95, v102, v106
	v_cvt_pk_bf16_f32 v96, v104, v100
	v_cvt_pk_bf16_f32 v97, v92, v88
	s_mov_b32 s8, 0
	s_cselect_b64 s[64:65], -1, 0
	v_mov_b32_e32 v203, v232
	v_mov_b32_e32 v205, v231
	s_mov_b32 s87, 0
	ds_write_b128 v233, v[94:97] offset:4096
	ds_write_b128 v234, v[84:87] offset:16384
	ds_write_b128 v234, v[80:83] offset:16400
	s_waitcnt lgkmcnt(0)
	s_barrier
	s_or_b64 s[6:7], s[58:59], s[64:65]
	s_or_b64 s[6:7], s[6:7], s[2:3]
	s_cmp_eq_u64 s[6:7], 0
	s_cbranch_scc1 .Lfx_entry

.Lfx_entry:
	v_mov_b32_e32 v237, v112
	v_mov_b32_e32 v236, v113
	ds_read_b128 v[176:179], v203
	ds_read_b128 v[180:183], v203 offset:4096
	ds_read_b128 v[184:187], v203 offset:8192
	ds_read_b128 v[188:191], v203 offset:12288
.Lfx_loop:
	ds_read_b64_tr_b16 v[96:97], v205 offset:16384
	ds_read_b64_tr_b16 v[98:99], v205 offset:16896
	ds_read_b64_tr_b16 v[100:101], v205 offset:17408
	ds_read_b64_tr_b16 v[102:103], v205 offset:17920
	ds_read_b64_tr_b16 v[104:105], v205 offset:24576
	ds_read_b64_tr_b16 v[106:107], v205 offset:25088
	ds_read_b64_tr_b16 v[108:109], v205 offset:25600
	ds_read_b64_tr_b16 v[110:111], v205 offset:26112
	s_waitcnt lgkmcnt(8)
	v_mfma_f32_32x32x16_bf16 v[80:95], v[176:179], v[128:131], v[48:63]
	v_mfma_f32_32x32x16_bf16 v[80:95], v[180:183], v[132:135], v[80:95]
	v_mfma_f32_32x32x16_bf16 v[80:95], v[184:187], v[136:139], v[80:95]
	v_mfma_f32_32x32x16_bf16 v[80:95], v[188:191], v[140:143], v[80:95]
	v_mfma_f32_32x32x16_bf16 v[112:127], v[176:179], v[144:147], v[48:63]
	v_mfma_f32_32x32x16_bf16 v[112:127], v[180:183], v[148:151], v[112:127]
	v_mfma_f32_32x32x16_bf16 v[112:127], v[184:187], v[152:155], v[112:127]
	v_mfma_f32_32x32x16_bf16 v[112:127], v[188:191], v[156:159], v[112:127]
	v_add_u32_e32 v203, 0x200, v203
	s_add_i32 s8, s8, 32
	s_add_i32 s87, s87, 1
	s_nop 4
	v_exp_f32_e32 v80, v80
	v_exp_f32_e32 v81, v81
	v_exp_f32_e32 v82, v82
	v_exp_f32_e32 v83, v83
	v_exp_f32_e32 v84, v84
	v_add_f32_e32 v240, v80, v81
	v_exp_f32_e32 v85, v85
	v_add_f32_e32 v240, v240, v82
	v_exp_f32_e32 v86, v86
	v_add_f32_e32 v240, v240, v83
	v_exp_f32_e32 v87, v87
	v_add_f32_e32 v241, v84, v85
	v_exp_f32_e32 v88, v88
	v_add_f32_e32 v241, v241, v86
	v_exp_f32_e32 v89, v89
	v_add_f32_e32 v241, v241, v87
	v_exp_f32_e32 v90, v90
	v_exp_f32_e32 v91, v91
	v_add_f32_e32 v242, v88, v89
	v_exp_f32_e32 v92, v92
	v_add_f32_e32 v242, v242, v90
	v_exp_f32_e32 v93, v93
	v_add_f32_e32 v242, v242, v91
	v_exp_f32_e32 v94, v94
	v_exp_f32_e32 v95, v95
	v_add_f32_e32 v243, v92, v93
	v_add_f32_e32 v240, v240, v241
	v_add_f32_e32 v243, v243, v94
	v_add_f32_e32 v243, v243, v95
	v_add_f32_e32 v242, v242, v243
	v_add_f32_e32 v240, v240, v242
	v_add_f32_e32 v237, v237, v240
	s_waitcnt lgkmcnt(0)
	s_cmp_eq_u32 s8, 0x80
	s_cbranch_scc1 .Lfx_nopref
	ds_read_b128 v[176:179], v203
	ds_read_b128 v[180:183], v203 offset:4096
	ds_read_b128 v[184:187], v203 offset:8192
	ds_read_b128 v[188:191], v203 offset:12288
.Lfx_nopref:
	v_cvt_pk_bf16_f32 v80, v80, v81
	v_cvt_pk_bf16_f32 v81, v82, v83
	v_cvt_pk_bf16_f32 v82, v84, v85
	v_cvt_pk_bf16_f32 v83, v86, v87
	v_cvt_pk_bf16_f32 v84, v88, v89
	v_cvt_pk_bf16_f32 v85, v90, v91
	v_cvt_pk_bf16_f32 v86, v92, v93
	v_cvt_pk_bf16_f32 v87, v94, v95
	v_mfma_f32_32x32x16_bf16 v[64:79], v[96:99], v[80:83], v[64:79]
	v_mfma_f32_32x32x16_bf16 v[32:47], v[104:107], v[80:83], v[32:47]
	v_mfma_f32_32x32x16_bf16 v[64:79], v[100:103], v[84:87], v[64:79]
	v_mfma_f32_32x32x16_bf16 v[32:47], v[108:111], v[84:87], v[32:47]
	v_exp_f32_e32 v112, v112
	v_exp_f32_e32 v113, v113
	v_exp_f32_e32 v114, v114
	v_exp_f32_e32 v115, v115
	v_exp_f32_e32 v116, v116
	v_add_f32_e32 v240, v112, v113
	v_exp_f32_e32 v117, v117
	v_add_f32_e32 v240, v240, v114
	v_exp_f32_e32 v118, v118
	v_add_f32_e32 v240, v240, v115
	v_exp_f32_e32 v119, v119
	v_add_f32_e32 v241, v116, v117
	v_exp_f32_e32 v120, v120
	v_add_f32_e32 v241, v241, v118
	v_exp_f32_e32 v121, v121
	v_add_f32_e32 v241, v241, v119
	v_exp_f32_e32 v122, v122
	v_exp_f32_e32 v123, v123
	v_add_f32_e32 v242, v120, v121
	v_exp_f32_e32 v124, v124
	v_add_f32_e32 v242, v242, v122
	v_exp_f32_e32 v125, v125
	v_add_f32_e32 v242, v242, v123
	v_exp_f32_e32 v126, v126
	v_exp_f32_e32 v127, v127
	v_add_f32_e32 v243, v124, v125
	v_add_f32_e32 v240, v240, v241
	v_add_f32_e32 v243, v243, v126
	v_add_f32_e32 v243, v243, v127
	v_add_f32_e32 v242, v242, v243
	v_add_f32_e32 v240, v240, v242
	v_add_f32_e32 v227, v227, v240
	v_cvt_pk_bf16_f32 v112, v112, v113
	v_cvt_pk_bf16_f32 v113, v114, v115
	v_cvt_pk_bf16_f32 v114, v116, v117
	v_cvt_pk_bf16_f32 v115, v118, v119
	v_cvt_pk_bf16_f32 v116, v120, v121
	v_cvt_pk_bf16_f32 v117, v122, v123
	v_cvt_pk_bf16_f32 v118, v124, v125
	v_cvt_pk_bf16_f32 v119, v126, v127
	v_mfma_f32_32x32x16_bf16 v[16:31], v[96:99], v[112:115], v[16:31]
	v_mfma_f32_32x32x16_bf16 v[0:15], v[104:107], v[112:115], v[0:15]
	v_mfma_f32_32x32x16_bf16 v[16:31], v[100:103], v[116:119], v[16:31]
	v_mfma_f32_32x32x16_bf16 v[0:15], v[108:111], v[116:119], v[0:15]
	v_add_u32_e32 v205, 0x800, v205
	s_cmp_lg_u32 s8, 0x80
	s_cbranch_scc1 .Lfx_loop
	s_nop 7
	s_branch .LBB0_406
